# SWA items claimed dynamically in groups of 8 heads from a grid-wide counter: workgroups on faster XCDs that finish the dense attention early take more groups
# speedup vs baseline: 1.0062x; 1.0062x over previous
; #define LAS __attribute__((address_space(3)))
; __global__ void __launch_bounds__(512) fwd_mega(Args a) {
;     extern __shared__ __attribute__((aligned(16))) unsigned char lds_raw[];
;     LAS unsigned char* lds = (LAS unsigned char*)lds_raw;
;     cg::grid_group grid = cg::this_grid();
;     const int tid = threadIdx.x, lane = tid & 63, wave = __builtin_amdgcn_readfirstlane(tid >> 6);
;     const int G = gridDim.x, bx = blockIdx.x;
;     const int vcu = (G % 8 == 0) ? (bx % 8) * (G / 8) + bx / 8 : bx;
;     unsigned char* ws = a.ws;
_Z8fwd_mega4Args:
	s_load_dwordx16 s[72:87], s[0:1], 0x0
	s_load_dwordx8 s[24:31], s[0:1], 0x80
	s_load_dwordx4 s[52:55], s[0:1], 0xa0
	s_load_dword s3, s[0:1], 0xb0
	s_add_u32 s58, s0, 0xb0
	s_mov_b32 s60, s2
	s_addc_u32 s59, s1, 0
	v_and_b32_e32 v162, 0x3ff, v0
	s_waitcnt lgkmcnt(0)
	s_cmp_eq_u32 s60, 0
	s_cbranch_scc0 .Lsm_init_done
	v_and_b32_e32 v254, 7, v162
	v_lshlrev_b32_e32 v254, 8, v254
	v_add_u32_e32 v254, 0x400, v254
	v_mov_b32_e32 v255, 0
	global_store_dword v254, v255, s[52:53]
	v_mov_b32_e32 v254, 0xc00
	global_store_dword v254, v255, s[52:53]

; template <bool MLA> __device__ __forceinline__ void attn_unit(const AttnP& P, int b, int hh, int qb, LAS char* lds) {
;     constexpr int DV = MLA ? 128 : 64, NCB = DV / 32, NQF = MLA ? 12 : 4;
;     constexpr int KBYTES = MLA ? 24576 : 8192, VBYTES = 64 * DV * 2;
;     constexpr int SC9 = MLA ? 72168784 : 125000000;
;     constexpr float SCALE = SC9 * 1e-9f;
;     constexpr int W = MLA ? (1 << 30) : 128;
;     const int tid = threadIdx.x, wid = __builtin_amdgcn_readfirstlane(tid >> 6), lane = tid & 63, r32 = lane & 31, hi = lane >> 5;
;     LAS char* V_lds = lds; LAS char* K_lds = lds + 2 * VBYTES;
;     LAS float* ws = (LAS float*)(lds + 2 * VBYTES + 2 * KBYTES) + wid * 64; LAS float* li_l = ws; LAS float* al_l = ws + 32;
;     LAS float* bias_l = (LAS float*)(lds + 2 * VBYTES + 2 * KBYTES + 2048);
;     const int q0 = qb * 256; const size_t rowbase = (size_t)b * SEQ;
;     const int jt0 = MLA ? 0 : (q0 == 0 ? 0 : -2);
;     const int NT = MLA ? 4 * qb + 4 : 4 - jt0;
;     const int kbase0 = MLA ? 0 : q0 + 64 * jt0;
;     const int qlo = q0 + wid * 32, qm = qlo + r32 - 4 * hi;
;     bf16x8 qr[NQF];
;     const size_t qrow = rowbase + qlo + r32;
;     if constexpr (MLA) {
; #pragma unroll
;         for (int d0 = 0; d0 < 8; ++d0) qr[d0] = *(const bf16x8*)(P.QN + qrow * 2048 + hh * 128 + d0 * 16 + hi * 8);
; #pragma unroll
;         for (int d0 = 0; d0 < 4; ++d0) qr[8 + d0] = *(const bf16x8*)(P.QR + qrow * 1024 + hh * 64 + d0 * 16 + hi * 8);
;     } else {
; #pragma unroll
;         for (int d0 = 0; d0 < 4; ++d0) qr[d0] = *(const bf16x8*)(P.QS + qrow * 2048 + hh * 64 + d0 * 16 + hi * 8);
;         if (tid < 128) bias_l[tid] = P.rel[(int)T5B[tid] * 32 + hh] * (1.0f / SCALE);
;     }
;     bf16x8 sk0, sv0;
;     const int sr8 = tid >> 3, ch8 = tid & 7;
;     const bf16_t* Kg; const bf16_t* Vg; const bf16_t* Rg = nullptr;
;     unsigned okA = 0, okB = 0, orp = 0, ovA = 0, ovB = 0;
;     if constexpr (MLA) {
;         Kg = P.KN + rowbase * 2048 + hh * 128; Vg = P.V + rowbase * 2048 + hh * 128; Rg = P.KR + rowbase * 64;
;         { const int rA = 4 * wid + (lane >> 4), rB = rA + 32, cp = lane & 15; okA = (unsigned)(rA * 2048 + ((cp ^ (rA & 7)) << 3)); okB = (unsigned)(rB * 2048 + ((cp ^ (rB & 7)) << 3)); }
;         { const int rr = 8 * wid + (lane >> 3), cp = lane & 7; orp = (unsigned)(rr * 64 + ((cp ^ (rr & 7)) << 3)); }
.LBB0_597:
	v_readlane_b32 s64, v253, 0
	s_cmpk_gt_i32 s2, 0xfff
	v_readlane_b32 s68, v253, 4
	v_readlane_b32 s69, v253, 5
	v_readlane_b32 s70, v253, 6
	v_readlane_b32 s71, v253, 7
	v_readlane_b32 s65, v253, 1
	v_readlane_b32 s66, v253, 2
	v_readlane_b32 s67, v253, 3
	v_readlane_b32 s72, v253, 8
	v_readlane_b32 s73, v253, 9
	v_readlane_b32 s74, v253, 10
	v_readlane_b32 s75, v253, 11
	v_readlane_b32 s76, v253, 12
	v_readlane_b32 s77, v253, 13
	v_readlane_b32 s78, v253, 14
	v_readlane_b32 s79, v253, 15
	s_cbranch_scc1 .LBB0_682
	v_readlane_b32 s46, v253, 44
	v_readlane_b32 s47, v253, 45
	v_readlane_b32 s48, v253, 46
	v_readlane_b32 s49, v253, 47
	v_readfirstlane_b32 s4, v162
	s_nop 3
	s_lshr_b32 s4, s4, 6
	s_mov_b32 s29, 0x3e38aa3b
	v_mov_b32_e32 v238, 0xff800000
	v_and_b32_e32 v240, 15, v206
	v_lshrrev_b32_e32 v241, 4, v206
	v_and_b32_e32 v242, 7, v240
	v_xor_b32_e32 v242, v242, v241
	v_lshlrev_b32_e32 v242, 4, v242
	v_lshl_or_b32 v228, v240, 7, v242
	v_xor_b32_e32 v229, 64, v228
	v_add_u32_e32 v228, 49152, v228
	v_add_u32_e32 v229, 49152, v229
	v_and_b32_e32 v242, 1, v241
	v_lshrrev_b32_e32 v243, 1, v241
	v_lshlrev_b32_e32 v243, 8, v243
	v_lshl_or_b32 v243, v242, 10, v243
	v_lshrrev_b32_e32 v244, 2, v240
	v_lshl_or_b32 v243, v244, 6, v243
	v_and_b32_e32 v244, 3, v240
	v_lshl_or_b32 v243, v244, 3, v243
	v_lshlrev_b32_e32 v242, 5, v242
	v_or_b32_e32 v230, v243, v242
	v_xor_b32_e32 v242, 32, v242
	v_or_b32_e32 v231, v243, v242
	v_lshlrev_b32_e32 v242, 2, v241
	v_sub_u32_e32 v235, v240, v242
	v_lshlrev_b32_e32 v232, 2, v235
	v_add_u32_e32 v232, 98288, v232
	v_xor_b32_e32 v236, 16, v206
	v_lshlrev_b32_e32 v236, 2, v236
	v_xor_b32_e32 v237, 32, v206
	v_lshlrev_b32_e32 v237, 2, v237
	v_lshlrev_b32_e32 v242, 4, v241
	v_lshl_or_b32 v233, v240, 12, v242
	v_add_u32_e32 v196, 0x10000, v233
	v_lshlrev_b32_e32 v242, 3, v241
	v_lshl_or_b32 v234, v240, 12, v242
	v_add_u32_e32 v197, 0x10000, v234
	v_lshrrev_b32_e32 v240, 3, v162
	v_and_b32_e32 v241, 7, v162
	v_lshlrev_b32_e32 v242, 4, v241
	v_lshl_or_b32 v147, v240, 9, v242
	v_and_b32_e32 v242, 7, v240
	v_xor_b32_e32 v242, v242, v241
	v_lshlrev_b32_e32 v242, 4, v242
	v_lshl_or_b32 v148, v240, 7, v242
	v_add_u32_e32 v148, 49152, v148
	v_bfe_u32 v242, v240, 2, 1
	v_bfe_u32 v243, v240, 3, 1
	v_and_b32_e32 v244, 3, v240
	v_lshl_or_b32 v244, v243, 2, v244
	v_lshrrev_b32_e32 v245, 4, v240
	v_lshl_or_b32 v245, v245, 1, v242
	v_lshrrev_b32_e32 v246, 2, v241
	v_lshl_or_b32 v245, v245, 1, v246
	v_lshlrev_b32_e32 v245, 9, v245
	v_lshl_or_b32 v245, v244, 6, v245
	v_and_b32_e32 v246, 3, v241
	v_lshlrev_b32_e32 v246, 4, v246
	v_lshlrev_b32_e32 v242, 5, v242
	v_xor_b32_e32 v246, v246, v242
	v_or_b32_e32 v149, v245, v246
	s_getpc_b64 s[100:101]
	s_add_u32 s100, s100, _ZN3attL3T5BE@rel32@lo+4
	s_addc_u32 s101, s101, _ZN3attL3T5BE@rel32@hi+12
	v_mov_b32_e32 v150, 0
	v_cmp_gt_u32_e32 vcc, 0x80, v162
	s_nop 1
	s_and_saveexec_b64 s[0:1], vcc
	global_load_ubyte v150, v162, s[100:101]
	s_or_b64 exec, exec, s[0:1]
	v_lshlrev_b32_e32 v152, 2, v162
	v_add_u32_e32 v152, 98304, v152
	v_and_b32_e32 v153, 7, v206
	v_lshlrev_b32_e32 v153, 2, v153
	s_waitcnt vmcnt(0)
	v_lshlrev_b32_e32 v150, 7, v150
	v_mov_b32_e32 v248, 0x1a000
	s_cmp_eq_u32 s4, 0
	s_cbranch_scc0 .Lsw_na0
	s_mov_b64 s[100:101], exec
	s_mov_b64 exec, 1
	v_mov_b32_e32 v163, 0xc00
	v_mov_b32_e32 v1, 1
	global_atomic_add v239, v163, v1, s[52:53] sc0
	s_mov_b64 exec, s[100:101]
.Lsw_na0:
.Lsw_fetch:
	s_waitcnt lgkmcnt(0)
	s_barrier
	s_cmp_eq_u32 s4, 0
	s_cbranch_scc0 .Lsw_nb
	s_waitcnt vmcnt(0)
	v_readfirstlane_b32 s13, v239
	s_nop 3
	v_mov_b32_e32 v163, s13
	ds_write_b32 v248, v163
.Lsw_nb:
	s_waitcnt lgkmcnt(0)
	s_barrier
	ds_read_b32 v163, v248
	s_waitcnt lgkmcnt(0)
	v_readfirstlane_b32 s13, v163
	s_nop 3
	s_cmp_lt_u32 s13, 0x200
	s_cbranch_scc0 .Lsw_end
	s_and_b32 s2, s13, 0xff
	s_lshr_b32 s14, s13, 8
	s_lshl_b32 s14, s14, 11
	s_or_b32 s2, s2, s14
	s_and_b32 s5, s2, 63
	s_bfe_u32 s7, s2, 0x20006
	s_bfe_u32 s6, s2, 0x30008
	s_lshr_b32 s8, s2, 11
	s_lshl_b32 s9, s7, 3
	s_or_b32 s9, s9, s6
	s_lshl_b32 s13, s8, 14
	s_lshl_b32 s14, s5, 8
	s_add_u32 s13, s13, s14
	s_lshl_b32 s14, s4, 5
	s_add_u32 s13, s13, s14
	s_lshl_b32 s13, s13, 12
	s_lshl_b32 s14, s9, 7
	s_add_u32 s13, s13, s14
	s_add_u32 s64, s18, s13
	s_addc_u32 s65, s19, 0
	global_load_dwordx4 v[18:21], v233, s[64:65] offset:0
	global_load_dwordx4 v[22:25], v233, s[64:65] offset:64
	global_load_dwordx4 v[26:29], v196, s[64:65] offset:0
	global_load_dwordx4 v[30:33], v196, s[64:65] offset:64
.Lsw_item:
	s_and_b32 s5, s2, 63
	s_bfe_u32 s7, s2, 0x20006
	s_bfe_u32 s6, s2, 0x30008
	s_lshr_b32 s8, s2, 11
	s_lshl_b32 s9, s7, 3
	s_or_b32 s9, s9, s6
	s_mov_b64 s[50:51], s[64:65]
	s_cmp_eq_u32 s6, 0
	s_cbranch_scc1 .Lsw_nowait
	s_waitcnt vmcnt(8)
.Lsw_nowait:
	s_cmp_lg_u32 s6, 0
	s_cbranch_scc1 .Lsw_staged
	s_waitcnt lgkmcnt(0)
	s_barrier
	s_cmp_eq_u32 s5, 0
	s_cselect_b32 s57, 4, 6
	s_cselect_b32 s14, 0, 0x80
	s_lshl_b32 s13, s8, 14
	s_lshl_b32 s15, s5, 8
	s_add_u32 s13, s13, s15
	s_sub_u32 s13, s13, s14
	s_lshl_b32 s13, s13, 9
	s_lshl_b32 s14, s7, 7
	s_add_u32 s13, s13, s14
	s_add_u32 s36, s46, s13
	s_addc_u32 s37, s47, 0
	s_add_u32 s38, s48, s13
	s_addc_u32 s39, s49, 0
	global_load_dwordx4 v[70:73], v147, s[36:37]
	global_load_dwordx4 v[74:77], v147, s[38:39]
	s_add_u32 s36, s36, 0x8000
	s_addc_u32 s37, s37, 0
	s_add_u32 s38, s38, 0x8000
	s_addc_u32 s39, s39, 0
	global_load_dwordx4 v[78:81], v147, s[36:37]
	global_load_dwordx4 v[82:85], v147, s[38:39]
	s_add_u32 s36, s36, 0x8000
	s_addc_u32 s37, s37, 0
	s_add_u32 s38, s38, 0x8000
	s_addc_u32 s39, s39, 0
	global_load_dwordx4 v[86:89], v147, s[36:37]
	global_load_dwordx4 v[90:93], v147, s[38:39]
	s_add_u32 s36, s36, 0x8000
	s_addc_u32 s37, s37, 0
	s_add_u32 s38, s38, 0x8000
	s_addc_u32 s39, s39, 0
	global_load_dwordx4 v[94:97], v147, s[36:37]
	global_load_dwordx4 v[98:101], v147, s[38:39]
	s_add_u32 s36, s36, 0x8000
	s_addc_u32 s37, s37, 0
	s_add_u32 s38, s38, 0x8000
	s_addc_u32 s39, s39, 0
	s_cmp_eq_u32 s57, 4
	s_cbranch_scc1 .Lsw_ld_done
	global_load_dwordx4 v[102:105], v147, s[36:37]
	global_load_dwordx4 v[106:109], v147, s[38:39]
	s_add_u32 s36, s36, 0x8000
	s_addc_u32 s37, s37, 0
	s_add_u32 s38, s38, 0x8000
	s_addc_u32 s39, s39, 0
	global_load_dwordx4 v[110:113], v147, s[36:37]
	global_load_dwordx4 v[114:117], v147, s[38:39]

; template <bool MLA> __device__ __forceinline__ void attn_unit(const AttnP& P, int b, int hh, int qb, LAS char* lds) {
;     ...
;         for (int d0 = 0; d0 < 4; ++d0) qr[d0] = *(const bf16x8*)(P.QS + qrow * 2048 + hh * 64 + d0 * 16 + hi * 8);
;         if (tid < 128) bias_l[tid] = P.rel[(int)T5B[tid] * 32 + hh] * (1.0f / SCALE);
;     }
;     bf16x8 sk0, sv0;
;     const int sr8 = tid >> 3, ch8 = tid & 7;
;     const bf16_t* Kg; const bf16_t* Vg; const bf16_t* Rg = nullptr;
;     unsigned okA = 0, okB = 0, orp = 0, ovA = 0, ovB = 0;
;     if constexpr (MLA) {
;         Kg = P.KN + rowbase * 2048 + hh * 128; Vg = P.V + rowbase * 2048 + hh * 128; Rg = P.KR + rowbase * 64;
;         { const int rA = 4 * wid + (lane >> 4), rB = rA + 32, cp = lane & 15; okA = (unsigned)(rA * 2048 + ((cp ^ (rA & 7)) << 3)); okB = (unsigned)(rB * 2048 + ((cp ^ (rB & 7)) << 3)); }
;         { const int rr = 8 * wid + (lane >> 3), cp = lane & 7; orp = (unsigned)(rr * 64 + ((cp ^ (rr & 7)) << 3)); }
;         { const int stA = 2 * wid + (lane >> 5), stB = stA + 16; const int kl = (lane & 31) >> 2, c8 = 8 * (lane & 3);
;           const int kkA = (stA >> 2) * 8 + kl, kkB = (stB >> 2) * 8 + kl;
;           const int kA = (kkA & ~0xC) | ((kkA & 4) << 1) | ((kkA & 8) >> 1), kB = (kkB & ~0xC) | ((kkB & 4) << 1) | ((kkB & 8) >> 1);
;           ovA = (unsigned)(kA * 2048 + 32 * (stA & 3) + c8); ovB = (unsigned)(kB * 2048 + 32 * (stB & 3) + c8); }
;     } else { Kg = P.KS + (rowbase + sr8) * 256 + (hh >> 3) * 64 + ch8 * 8; Vg = P.VS + (rowbase + sr8) * 256 + (hh >> 3) * 64 + ch8 * 8; }
;     const int kws = KSWZ64(sr8, ch8), vst0 = v_st<NCB>(sr8, ch8 * 8);
;     ...
;     float m_reg = MLA ? 0.f : P.sinks[hh] * (1.0f / SCALE), l_reg = MLA ? 0.f : 1.f;
;     f32x16 o[NCB];
; #pragma unroll
;     for (int d = 0; d < NCB; ++d) o[d] = f32x16{};
;     const int vb0 = (int)(uintptr_t)V_lds + v_rd_base(lane);
;     LOADT(0, 0); asm volatile("s_waitcnt vmcnt(0)" ::: "memory"); WRITET(0); __syncthreads();
;     for (int t = 0; t < NT; ++t) {
;         const int buf = t & 1;
;         if (t + 1 < NT) LOADT(t + 1, buf ^ 1);
;         const int kb = kbase0 + 64 * t;
; __global__ void __launch_bounds__(512) fwd_mega(Args a) {
;     ...
;         for (int it = vcu; it < 4096; it += G) { const int qb = it & 63, hq = (it >> 6) & 31, b = it >> 11;
;             att::attn_unit<false>(P, b, hq, qb, (LAS char*)lds); }
.Lsw_staged:
	v_mov_b32_e32 v2, v18
	v_mov_b32_e32 v3, v19
	v_mov_b32_e32 v4, v20
	v_mov_b32_e32 v5, v21
	v_mov_b32_e32 v6, v22
	v_mov_b32_e32 v7, v23
	v_mov_b32_e32 v8, v24
	v_mov_b32_e32 v9, v25
	v_mov_b32_e32 v10, v26
	v_mov_b32_e32 v11, v27
	v_mov_b32_e32 v12, v28
	v_mov_b32_e32 v13, v29
	v_mov_b32_e32 v14, v30
	v_mov_b32_e32 v15, v31
	v_mov_b32_e32 v16, v32
	v_mov_b32_e32 v17, v33
	s_add_u32 s40, s2, 0x100
	s_cmp_lt_u32 s6, 7
	s_cbranch_scc0 .Lsw_last
	s_and_b32 s98, s40, 63
	s_bfe_u32 s100, s40, 0x20006
	s_bfe_u32 s99, s40, 0x30008
	s_lshr_b32 s101, s40, 11
	s_lshl_b32 s15, s100, 3
	s_or_b32 s15, s15, s99
	s_lshl_b32 s13, s101, 14
	s_lshl_b32 s14, s98, 8
	s_add_u32 s13, s13, s14
	s_lshl_b32 s14, s4, 5
	s_add_u32 s13, s13, s14
	s_lshl_b32 s13, s13, 12
	s_lshl_b32 s14, s15, 7
	s_add_u32 s13, s13, s14
	s_add_u32 s64, s18, s13
	s_addc_u32 s65, s19, 0
	global_load_dwordx4 v[18:21], v233, s[64:65] offset:0
	global_load_dwordx4 v[22:25], v233, s[64:65] offset:64
	global_load_dwordx4 v[26:29], v196, s[64:65] offset:0
	global_load_dwordx4 v[30:33], v196, s[64:65] offset:64
	s_branch .Lsw_nopf
.Lsw_last:
	s_cmp_eq_u32 s4, 0
	s_cbranch_scc0 .Lsw_na1
	s_mov_b64 s[100:101], exec
	s_mov_b64 exec, 1
	v_mov_b32_e32 v163, 0xc00
	v_mov_b32_e32 v1, 1
	global_atomic_add v239, v163, v1, s[52:53] sc0
	s_mov_b64 exec, s[100:101]
.Lsw_na1:
.Lsw_nopf:
	s_nop 3
	v_readlane_b32 s28, v151, s6
	s_lshl_b32 s33, s6, 9
	v_add_u32_e32 v146, s33, v232
	s_lshl_b32 s16, s4, 1
	s_cmp_eq_u32 s5, 0
	s_cselect_b32 s13, 8, 0
	s_sub_i32 s16, s16, s13
	ds_read_b32 v34, v146 offset:528
	ds_read_b32 v35, v146 offset:524
	ds_read_b32 v36, v146 offset:520
	ds_read_b32 v37, v146 offset:516
	ds_read_b32 v38, v146 offset:464
	ds_read_b32 v39, v146 offset:460
	ds_read_b32 v40, v146 offset:456
	ds_read_b32 v41, v146 offset:452
	ds_read_b32 v42, v146 offset:400
	ds_read_b32 v43, v146 offset:396
	ds_read_b32 v44, v146 offset:392
	ds_read_b32 v45, v146 offset:388
	ds_read_b32 v46, v146 offset:336
	ds_read_b32 v47, v146 offset:332
	ds_read_b32 v48, v146 offset:328
	ds_read_b32 v49, v146 offset:324
	ds_read_b32 v50, v146 offset:272
	ds_read_b32 v51, v146 offset:268
	ds_read_b32 v52, v146 offset:264
	ds_read_b32 v53, v146 offset:260
	ds_read_b32 v54, v146 offset:208
	ds_read_b32 v55, v146 offset:204
	ds_read_b32 v56, v146 offset:200
	ds_read_b32 v57, v146 offset:196
	ds_read_b32 v58, v146 offset:144
	ds_read_b32 v59, v146 offset:140
	ds_read_b32 v60, v146 offset:136
	ds_read_b32 v61, v146 offset:132
	ds_read_b32 v62, v146 offset:80
	ds_read_b32 v63, v146 offset:76
	ds_read_b32 v64, v146 offset:72
	ds_read_b32 v65, v146 offset:68
	ds_read_b32 v66, v146 offset:16
	ds_read_b32 v67, v146 offset:12
	ds_read_b32 v68, v146 offset:8
	ds_read_b32 v69, v146 offset:4
	v_mov_b32_e32 v164, 0
	v_mov_b32_e32 v165, 0
	v_mov_b32_e32 v166, 0
	v_mov_b32_e32 v167, 0
	v_mov_b32_e32 v168, 0
	v_mov_b32_e32 v169, 0
	v_mov_b32_e32 v170, 0
	v_mov_b32_e32 v171, 0
	v_mov_b32_e32 v172, 0
	v_mov_b32_e32 v173, 0
	v_mov_b32_e32 v174, 0
	v_mov_b32_e32 v175, 0
	v_mov_b32_e32 v176, 0
	v_mov_b32_e32 v177, 0
	v_mov_b32_e32 v178, 0
	v_mov_b32_e32 v179, 0
	v_mov_b32_e32 v180, 0
	v_mov_b32_e32 v181, 0
	v_mov_b32_e32 v182, 0
	v_mov_b32_e32 v183, 0
	v_mov_b32_e32 v184, 0
	v_mov_b32_e32 v185, 0
	v_mov_b32_e32 v186, 0
	v_mov_b32_e32 v187, 0
	v_mov_b32_e32 v188, 0
	v_mov_b32_e32 v189, 0
	v_mov_b32_e32 v190, 0
	v_mov_b32_e32 v191, 0
	v_mov_b32_e32 v192, 0
	v_mov_b32_e32 v193, 0
	v_mov_b32_e32 v194, 0
	v_mov_b32_e32 v195, 0
	v_mov_b32_e32 v224, 0
	v_mov_b32_e32 v225, 0
	v_mov_b32_e32 v226, 0
	v_mov_b32_e32 v227, 0
	s_waitcnt lgkmcnt(0)
	v_cmp_gt_i32_e32 vcc, 0, v235
	s_nop 1
	v_cndmask_b32_e32 v34, v238, v34, vcc
	v_cndmask_b32_e32 v66, v66, v238, vcc
	v_cmp_gt_i32_e32 vcc, 1, v235
	s_nop 1
	v_cndmask_b32_e32 v35, v238, v35, vcc
	v_cndmask_b32_e32 v67, v67, v238, vcc
	v_cmp_gt_i32_e32 vcc, 2, v235
	s_nop 1
	v_cndmask_b32_e32 v36, v238, v36, vcc
	v_cndmask_b32_e32 v68, v68, v238, vcc
	v_cmp_gt_i32_e32 vcc, 3, v235
	s_nop 1
	v_cndmask_b32_e32 v37, v238, v37, vcc
	v_cndmask_b32_e32 v69, v69, v238, vcc
	s_add_i32 s17, s16, 0
	s_max_i32 s17, s17, 0
	s_lshl_b32 s17, s17, 11
	v_add_u32_e32 v142, s17, v228
	v_add_u32_e32 v143, s17, v229
	ds_read_b128 v[208:211], v142 offset:0
	ds_read_b128 v[212:215], v143 offset:0
	ds_read_b128 v[216:219], v142 offset:2048
	ds_read_b128 v[220:223], v143 offset:2048
	s_waitcnt lgkmcnt(3)
; #define LAS __attribute__((address_space(3)))
; __device__ __forceinline__ void qk64(f32x16& p0, f32x16& p1, const LAS char* kl, int r32, int hi, const bf16x8* qr) {
; #pragma unroll
;     for (int ks = 0; ks < 4; ++ks) { const LAS char* a = kl + KSWZ64(r32, 2 * ks + hi);
;         const bf16x8 b0 = *reinterpret_cast<const LAS bf16x8*>(a);
;         const bf16x8 b1 = *reinterpret_cast<const LAS bf16x8*>(a + 32 * 128);
;         p0 = __builtin_amdgcn_mfma_f32_32x32x16_bf16(b0, qr[ks], p0, 0, 0, 0);
;         p1 = __builtin_amdgcn_mfma_f32_32x32x16_bf16(b1, qr[ks], p1, 0, 0, 0); }
; }
; template <bool MLA> __device__ __forceinline__ void attn_unit(const AttnP& P, int b, int hh, int qb, LAS char* lds) {
;     ...
;             else { qk64(p0, p1, K_lds + buf * KBYTES, r32, hi, qr); }
;             const int dq = qm - kb;
;             if constexpr (!MLA) {
; #pragma unroll
;                 for (int r = 0; r < 16; ++r) { const int c = (r & 3) + 8 * (r >> 2); p0[r] += bias_l[(dq - c) & 127]; p1[r] += bias_l[(dq - c - 32) & 127]; }
;             }
;             if (kb + 63 > qlo || (!MLA && kb <= qlo + 31 - W)) mask_tile(p0, p1, dq, (unsigned)W);
	v_mfma_f32_16x16x32_bf16 v[70:73], v[208:211], v[2:5], v[34:37]
	s_add_i32 s17, s16, 2
	s_max_i32 s17, s17, 0
	s_lshl_b32 s17, s17, 11
	v_add_u32_e32 v144, s17, v228
	v_add_u32_e32 v145, s17, v229
	ds_read_b128 v[208:211], v144 offset:0
	s_waitcnt lgkmcnt(3)
	v_mfma_f32_16x16x32_bf16 v[70:73], v[212:215], v[6:9], v[70:73]
	ds_read_b128 v[212:215], v145 offset:0
	s_waitcnt lgkmcnt(3)
	v_mfma_f32_16x16x32_bf16 v[74:77], v[216:219], v[2:5], v[38:41]
	v_mfma_f32_16x16x32_bf16 v[106:109], v[216:219], v[10:13], v[34:37]
	ds_read_b128 v[216:219], v144 offset:2048
	s_waitcnt lgkmcnt(3)
	v_mfma_f32_16x16x32_bf16 v[74:77], v[220:223], v[6:9], v[74:77]
	v_mfma_f32_16x16x32_bf16 v[106:109], v[220:223], v[14:17], v[106:109]
	ds_read_b128 v[220:223], v145 offset:2048
	s_waitcnt lgkmcnt(3)
	v_mfma_f32_16x16x32_bf16 v[78:81], v[208:211], v[2:5], v[42:45]
	v_mfma_f32_16x16x32_bf16 v[110:113], v[208:211], v[10:13], v[38:41]
	s_add_i32 s17, s16, 4
	s_max_i32 s17, s17, 0
	s_lshl_b32 s17, s17, 11
	v_add_u32_e32 v158, s17, v228
	v_add_u32_e32 v159, s17, v229
	ds_read_b128 v[208:211], v158 offset:0
	s_waitcnt lgkmcnt(3)
	v_mfma_f32_16x16x32_bf16 v[78:81], v[212:215], v[6:9], v[78:81]
	v_mfma_f32_16x16x32_bf16 v[110:113], v[212:215], v[14:17], v[110:113]
	ds_read_b128 v[212:215], v159 offset:0
	s_waitcnt lgkmcnt(3)
	v_mfma_f32_16x16x32_bf16 v[82:85], v[216:219], v[2:5], v[46:49]
	v_mfma_f32_16x16x32_bf16 v[114:117], v[216:219], v[10:13], v[42:45]
	ds_read_b128 v[216:219], v158 offset:2048
	s_waitcnt lgkmcnt(3)
	v_mfma_f32_16x16x32_bf16 v[82:85], v[220:223], v[6:9], v[82:85]
	v_mfma_f32_16x16x32_bf16 v[114:117], v[220:223], v[14:17], v[114:117]
	ds_read_b128 v[220:223], v159 offset:2048
	s_waitcnt lgkmcnt(3)
	v_mfma_f32_16x16x32_bf16 v[86:89], v[208:211], v[2:5], v[50:53]
	v_mfma_f32_16x16x32_bf16 v[118:121], v[208:211], v[10:13], v[46:49]
	s_add_i32 s17, s16, 6
	s_max_i32 s17, s17, 0
	s_lshl_b32 s17, s17, 11
	v_add_u32_e32 v160, s17, v228
	v_add_u32_e32 v161, s17, v229
	ds_read_b128 v[208:211], v160 offset:0
	s_waitcnt lgkmcnt(3)
	v_mfma_f32_16x16x32_bf16 v[86:89], v[212:215], v[6:9], v[86:89]
	v_mfma_f32_16x16x32_bf16 v[118:121], v[212:215], v[14:17], v[118:121]
	ds_read_b128 v[212:215], v161 offset:0
	s_waitcnt lgkmcnt(3)
	v_mfma_f32_16x16x32_bf16 v[90:93], v[216:219], v[2:5], v[54:57]
	v_mfma_f32_16x16x32_bf16 v[122:125], v[216:219], v[10:13], v[50:53]
	ds_read_b128 v[216:219], v160 offset:2048
	s_waitcnt lgkmcnt(3)
	v_mfma_f32_16x16x32_bf16 v[90:93], v[220:223], v[6:9], v[90:93]
	v_mfma_f32_16x16x32_bf16 v[122:125], v[220:223], v[14:17], v[122:125]
	ds_read_b128 v[220:223], v161 offset:2048
	s_waitcnt lgkmcnt(3)
	v_mfma_f32_16x16x32_bf16 v[94:97], v[208:211], v[2:5], v[58:61]
	v_mfma_f32_16x16x32_bf16 v[126:129], v[208:211], v[10:13], v[54:57]
	s_add_i32 s17, s16, 8
	s_max_i32 s17, s17, 0
	s_lshl_b32 s17, s17, 11
	v_add_u32_e32 v204, s17, v228
	v_add_u32_e32 v207, s17, v229
	ds_read_b128 v[208:211], v204 offset:0
	s_waitcnt lgkmcnt(3)
	v_mfma_f32_16x16x32_bf16 v[94:97], v[212:215], v[6:9], v[94:97]
	v_mfma_f32_16x16x32_bf16 v[126:129], v[212:215], v[14:17], v[126:129]
	ds_read_b128 v[212:215], v207 offset:0
	s_waitcnt lgkmcnt(3)
	v_mfma_f32_16x16x32_bf16 v[98:101], v[216:219], v[2:5], v[62:65]
	v_mfma_f32_16x16x32_bf16 v[130:133], v[216:219], v[10:13], v[58:61]
	ds_read_b128 v[216:219], v204 offset:2048
	s_waitcnt lgkmcnt(3)
	v_mfma_f32_16x16x32_bf16 v[98:101], v[220:223], v[6:9], v[98:101]
	v_mfma_f32_16x16x32_bf16 v[130:133], v[220:223], v[14:17], v[130:133]
	ds_read_b128 v[220:223], v207 offset:2048
	s_waitcnt lgkmcnt(3)
	v_mfma_f32_16x16x32_bf16 v[102:105], v[208:211], v[2:5], v[66:69]
	v_mfma_f32_16x16x32_bf16 v[134:137], v[208:211], v[10:13], v[62:65]
	s_waitcnt lgkmcnt(2)
	v_mfma_f32_16x16x32_bf16 v[102:105], v[212:215], v[6:9], v[102:105]
	v_mfma_f32_16x16x32_bf16 v[134:137], v[212:215], v[14:17], v[134:137]
	s_waitcnt lgkmcnt(1)
	v_mfma_f32_16x16x32_bf16 v[138:141], v[216:219], v[10:13], v[66:69]
	s_waitcnt lgkmcnt(0)
	v_mfma_f32_16x16x32_bf16 v[138:141], v[220:223], v[14:17], v[138:141]
	s_nop 7
	s_cmp_lt_i32 s16, 0
	s_cbranch_scc0 .Lsw_nofirst
	s_add_i32 s13, s16, 0
	s_cmp_lt_i32 s13, 0
	s_cbranch_scc0 .Lsw_nf_0_0
	v_mov_b32_e32 v70, v238
	v_mov_b32_e32 v71, v238
	v_mov_b32_e32 v72, v238
	v_mov_b32_e32 v73, v238

; template <int SCALE_E6> __device__ __forceinline__ void partialSM(f32x16& p0, f32x16& p1, float& m_reg, float& mn, float& alpha) {
;     constexpr float SCALE = SCALE_E6 * 1e-9f; constexpr float C2 = 1.4426950408889634f * SCALE;
;     float pmax = p0[0];
; #pragma unroll
;     for (int r = 1; r < 16; ++r) pmax = fmaxf(pmax, p0[r]);
; #pragma unroll
;     for (int r = 0; r < 16; ++r) pmax = fmaxf(pmax, p1[r]);
;     { auto rr = __builtin_amdgcn_permlane32_swap(__float_as_uint(pmax), __float_as_uint(pmax), false, false);
;       pmax = fmaxf(__uint_as_float(rr[0]), __uint_as_float(rr[1])); }
;     if (__builtin_expect(__all((pmax - m_reg) * SCALE <= THR), 1)) { mn = m_reg; alpha = 1.f; }
;     else { mn = fmaxf(m_reg, pmax); alpha = __builtin_amdgcn_exp2f((m_reg - mn) * C2); m_reg = mn; }
;     const float mnL = -mn * C2;
; #pragma unroll
;     for (int r = 0; r < 16; ++r) p0[r] = fmaf(p0[r], C2, mnL);
; #pragma unroll
;     for (int r = 0; r < 16; ++r) p1[r] = fmaf(p1[r], C2, mnL);
.Lsw_nf_1_8:
.Lsw_nofirst:
	v_max3_f32 v154, v70, v71, v72
	v_max3_f32 v154, v154, v73, v74
	v_max3_f32 v154, v154, v75, v76
	v_max3_f32 v154, v154, v77, v78
	v_max3_f32 v154, v154, v79, v80
	v_max3_f32 v154, v154, v81, v82
	v_max3_f32 v154, v154, v83, v84
	v_max3_f32 v154, v154, v85, v86
	v_max3_f32 v154, v154, v87, v88
	v_max3_f32 v154, v154, v89, v90
	v_max3_f32 v154, v154, v91, v92
	v_max3_f32 v154, v154, v93, v94
	v_max3_f32 v154, v154, v95, v96
	v_max3_f32 v154, v154, v97, v98
	v_max3_f32 v154, v154, v99, v100
	v_max3_f32 v154, v154, v101, v102
	v_max3_f32 v154, v154, v103, v104
	v_max_f32_e32 v154, v154, v105
	v_max3_f32 v155, v106, v107, v108
	v_max3_f32 v155, v155, v109, v110
	v_max3_f32 v155, v155, v111, v112
	v_max3_f32 v155, v155, v113, v114
	v_max3_f32 v155, v155, v115, v116
	v_max3_f32 v155, v155, v117, v118
	v_max3_f32 v155, v155, v119, v120
	v_max3_f32 v155, v155, v121, v122
	v_max3_f32 v155, v155, v123, v124
	v_max3_f32 v155, v155, v125, v126
	v_max3_f32 v155, v155, v127, v128
	v_max3_f32 v155, v155, v129, v130
	v_max3_f32 v155, v155, v131, v132
	v_max3_f32 v155, v155, v133, v134
	v_max3_f32 v155, v155, v135, v136
	v_max3_f32 v155, v155, v137, v138
	v_max3_f32 v155, v155, v139, v140
	v_max_f32_e32 v155, v155, v141
	ds_bpermute_b32 v240, v236, v154
	ds_bpermute_b32 v241, v236, v155
	s_waitcnt lgkmcnt(0)
	v_max_f32_e32 v154, v154, v240
	v_max_f32_e32 v155, v155, v241
	ds_bpermute_b32 v240, v237, v154
	ds_bpermute_b32 v241, v237, v155
	s_waitcnt lgkmcnt(0)
	v_max_f32_e32 v154, v154, v240
	v_max_f32_e32 v155, v155, v241
	v_max_f32_e32 v154, s28, v154
	v_mul_f32_e64 v156, -v154, s29
	v_max_f32_e32 v155, s28, v155
	v_mul_f32_e64 v157, -v155, s29
	v_fma_f32 v70, v70, s29, v156
	v_fma_f32 v71, v71, s29, v156
	v_fma_f32 v72, v72, s29, v156
	v_fma_f32 v73, v73, s29, v156
	v_fma_f32 v74, v74, s29, v156
	v_fma_f32 v75, v75, s29, v156
	v_fma_f32 v76, v76, s29, v156
	v_fma_f32 v77, v77, s29, v156
	v_fma_f32 v78, v78, s29, v156
	v_fma_f32 v79, v79, s29, v156
	v_fma_f32 v80, v80, s29, v156
	v_fma_f32 v81, v81, s29, v156
	v_fma_f32 v82, v82, s29, v156
	v_fma_f32 v83, v83, s29, v156
	v_fma_f32 v84, v84, s29, v156
	v_fma_f32 v85, v85, s29, v156
	v_fma_f32 v86, v86, s29, v156
	v_fma_f32 v87, v87, s29, v156
	v_fma_f32 v88, v88, s29, v156
	v_fma_f32 v89, v89, s29, v156
	v_fma_f32 v90, v90, s29, v156
	v_fma_f32 v91, v91, s29, v156
	v_fma_f32 v92, v92, s29, v156
	v_fma_f32 v93, v93, s29, v156
	v_fma_f32 v94, v94, s29, v156
	v_fma_f32 v95, v95, s29, v156
	v_fma_f32 v96, v96, s29, v156
	v_fma_f32 v97, v97, s29, v156
	v_fma_f32 v98, v98, s29, v156
	v_fma_f32 v99, v99, s29, v156
	v_fma_f32 v100, v100, s29, v156
	v_fma_f32 v101, v101, s29, v156
	v_fma_f32 v102, v102, s29, v156
	v_fma_f32 v103, v103, s29, v156
	v_fma_f32 v104, v104, s29, v156
	v_fma_f32 v105, v105, s29, v156
	v_fma_f32 v106, v106, s29, v157
	v_fma_f32 v107, v107, s29, v157
	v_fma_f32 v108, v108, s29, v157
	v_fma_f32 v109, v109, s29, v157
	v_fma_f32 v110, v110, s29, v157
	v_fma_f32 v111, v111, s29, v157
	v_fma_f32 v112, v112, s29, v157
	v_fma_f32 v113, v113, s29, v157
	v_fma_f32 v114, v114, s29, v157
	v_fma_f32 v115, v115, s29, v157
	v_fma_f32 v116, v116, s29, v157
	v_fma_f32 v117, v117, s29, v157
	v_fma_f32 v118, v118, s29, v157
	v_fma_f32 v119, v119, s29, v157
	v_fma_f32 v120, v120, s29, v157
	v_fma_f32 v121, v121, s29, v157
	v_fma_f32 v122, v122, s29, v157
	v_fma_f32 v123, v123, s29, v157
	v_fma_f32 v124, v124, s29, v157
	v_fma_f32 v125, v125, s29, v157
	v_fma_f32 v126, v126, s29, v157
	v_fma_f32 v127, v127, s29, v157
	v_fma_f32 v128, v128, s29, v157
	v_fma_f32 v129, v129, s29, v157
	v_fma_f32 v130, v130, s29, v157
	v_fma_f32 v131, v131, s29, v157
	v_fma_f32 v132, v132, s29, v157
	v_fma_f32 v133, v133, s29, v157
	v_fma_f32 v134, v134, s29, v157
	v_fma_f32 v135, v135, s29, v157
	v_fma_f32 v136, v136, s29, v157
	v_fma_f32 v137, v137, s29, v157
	v_fma_f32 v138, v138, s29, v157
	v_fma_f32 v139, v139, s29, v157
	v_fma_f32 v140, v140, s29, v157
	v_fma_f32 v141, v141, s29, v157
	v_exp_f32_e32 v70, v70
	v_exp_f32_e32 v71, v71
	v_exp_f32_e32 v72, v72
	v_exp_f32_e32 v73, v73
	v_exp_f32_e32 v74, v74
	v_exp_f32_e32 v75, v75
	v_exp_f32_e32 v76, v76
	v_exp_f32_e32 v77, v77
	v_exp_f32_e32 v78, v78
	v_exp_f32_e32 v79, v79
	v_exp_f32_e32 v80, v80
	v_exp_f32_e32 v81, v81
	v_exp_f32_e32 v82, v82
	v_exp_f32_e32 v83, v83
	v_exp_f32_e32 v84, v84
	v_exp_f32_e32 v85, v85
	v_exp_f32_e32 v86, v86
	v_exp_f32_e32 v87, v87
	v_exp_f32_e32 v88, v88
	v_exp_f32_e32 v89, v89
	v_exp_f32_e32 v90, v90
	v_exp_f32_e32 v91, v91
	v_exp_f32_e32 v92, v92
	v_exp_f32_e32 v93, v93
	v_exp_f32_e32 v94, v94
	v_exp_f32_e32 v95, v95
	v_exp_f32_e32 v96, v96
	v_exp_f32_e32 v97, v97
	v_exp_f32_e32 v98, v98
	v_exp_f32_e32 v99, v99
	v_exp_f32_e32 v100, v100
	v_exp_f32_e32 v101, v101
	v_exp_f32_e32 v102, v102
	v_exp_f32_e32 v103, v103
	v_exp_f32_e32 v104, v104
	v_exp_f32_e32 v105, v105
	v_exp_f32_e32 v106, v106
	v_exp_f32_e32 v107, v107
	v_exp_f32_e32 v108, v108
	v_exp_f32_e32 v109, v109
	v_exp_f32_e32 v110, v110
	v_exp_f32_e32 v111, v111
	v_exp_f32_e32 v112, v112
	v_exp_f32_e32 v113, v113
	v_exp_f32_e32 v114, v114
	v_exp_f32_e32 v115, v115
	v_exp_f32_e32 v116, v116
	v_exp_f32_e32 v117, v117
	v_exp_f32_e32 v118, v118
	v_exp_f32_e32 v119, v119
	v_exp_f32_e32 v120, v120
	v_exp_f32_e32 v121, v121
	v_exp_f32_e32 v122, v122
	v_exp_f32_e32 v123, v123
	v_exp_f32_e32 v124, v124
	v_exp_f32_e32 v125, v125
	v_exp_f32_e32 v126, v126
	v_exp_f32_e32 v127, v127
	v_exp_f32_e32 v128, v128
	v_exp_f32_e32 v129, v129
	v_exp_f32_e32 v130, v130
	v_exp_f32_e32 v131, v131
	v_exp_f32_e32 v132, v132
	v_exp_f32_e32 v133, v133
	v_exp_f32_e32 v134, v134
; #define PV_RD(S, d0) do { constexpr int b_ = (d0) * 512; TRRD(S##l0, b_); TRRD(S##h0, b_ + KS_ / 2); TRRD(S##l1, b_ + KS_); TRRD(S##h1, b_ + KS_ + KS_ / 2); TRRD(S##l2, b_ + 2 * KS_); TRRD(S##h2, b_ + 2 * KS_ + KS_ / 2); TRRD(S##l3, b_ + 3 * KS_); TRRD(S##h3, b_ + 3 * KS_ + KS_ / 2); } while (0)
; #define WL(n) do { asm volatile("s_waitcnt lgkmcnt(" #n ")" ::: "memory"); SBAR(); } while (0)
; __device__ __forceinline__ void finishSM(f32x16& p0, f32x16& p1, float alpha, float& l_reg, bf16x8& pa0, bf16x8& pa1, bf16x8& pa2, bf16x8& pa3) {
; #pragma unroll
;     for (int r = 0; r < 16; ++r) p1[r] = __builtin_amdgcn_exp2f(p1[r]);
;     float ps = 0;
; #pragma unroll
;     for (int r = 0; r < 16; ++r) ps += p0[r];
; #pragma unroll
;     for (int r = 0; r < 16; ++r) ps += p1[r];
;     { auto rr = __builtin_amdgcn_permlane32_swap(__float_as_uint(ps), __float_as_uint(ps), false, false);
;       ps = __uint_as_float(rr[0]) + __uint_as_float(rr[1]); }
;     l_reg = l_reg * alpha + ps;
;     ...
;     PK4(p0, 0, pa0); PK4(p0, 8, pa1); PK4(p1, 0, pa2); PK4(p1, 8, pa3);
; template <int NCB> __device__ __forceinline__ void pv_tile(f32x16* o, int vb, bf16x8 pa0, bf16x8 pa1, bf16x8 pa2, bf16x8 pa3) {
;     ...
;     constexpr int KS_ = NCB * 1024;
;     ...
;     s16x4 Al0, Al1, Al2, Al3, Ah0, Ah1, Ah2, Ah3, Bl0, Bl1, Bl2, Bl3, Bh0, Bh1, Bh2, Bh3;
;     PV_RD(A, 0); PV_RD(B, 1); WL(8); PV_MM(A, 0);
;     if constexpr (NCB == 4) { PV_RD(A, 2); WL(8); PV_MM(B, 1); PV_RD(B, 3); WL(8); PV_MM(A, 2); WL(0); PV_MM(B, 3); }
;     else { WL(0); PV_MM(B, 1); }
	v_exp_f32_e32 v135, v135
	v_exp_f32_e32 v136, v136
	v_exp_f32_e32 v137, v137
	v_exp_f32_e32 v138, v138
	v_exp_f32_e32 v139, v139
	v_exp_f32_e32 v140, v140
	v_exp_f32_e32 v141, v141
	v_pk_add_f32 v[224:225], v[224:225], v[70:71]
	v_pk_add_f32 v[226:227], v[226:227], v[106:107]
	v_pk_add_f32 v[224:225], v[224:225], v[72:73]
	v_pk_add_f32 v[226:227], v[226:227], v[108:109]
	v_pk_add_f32 v[224:225], v[224:225], v[74:75]
	v_pk_add_f32 v[226:227], v[226:227], v[110:111]
	v_pk_add_f32 v[224:225], v[224:225], v[76:77]
	v_pk_add_f32 v[226:227], v[226:227], v[112:113]
	v_pk_add_f32 v[224:225], v[224:225], v[78:79]
	v_pk_add_f32 v[226:227], v[226:227], v[114:115]
	v_pk_add_f32 v[224:225], v[224:225], v[80:81]
	v_pk_add_f32 v[226:227], v[226:227], v[116:117]
	v_pk_add_f32 v[224:225], v[224:225], v[82:83]
	v_pk_add_f32 v[226:227], v[226:227], v[118:119]
	v_pk_add_f32 v[224:225], v[224:225], v[84:85]
	v_pk_add_f32 v[226:227], v[226:227], v[120:121]
	v_pk_add_f32 v[224:225], v[224:225], v[86:87]
	v_pk_add_f32 v[226:227], v[226:227], v[122:123]
	v_pk_add_f32 v[224:225], v[224:225], v[88:89]
	v_pk_add_f32 v[226:227], v[226:227], v[124:125]
	v_pk_add_f32 v[224:225], v[224:225], v[90:91]
	v_pk_add_f32 v[226:227], v[226:227], v[126:127]
	v_pk_add_f32 v[224:225], v[224:225], v[92:93]
	v_pk_add_f32 v[226:227], v[226:227], v[128:129]
	v_pk_add_f32 v[224:225], v[224:225], v[94:95]
	v_pk_add_f32 v[226:227], v[226:227], v[130:131]
	v_pk_add_f32 v[224:225], v[224:225], v[96:97]
	v_pk_add_f32 v[226:227], v[226:227], v[132:133]
	v_pk_add_f32 v[224:225], v[224:225], v[98:99]
	v_pk_add_f32 v[226:227], v[226:227], v[134:135]
	v_pk_add_f32 v[224:225], v[224:225], v[100:101]
	v_pk_add_f32 v[226:227], v[226:227], v[136:137]
	v_pk_add_f32 v[224:225], v[224:225], v[102:103]
	v_pk_add_f32 v[226:227], v[226:227], v[138:139]
	v_pk_add_f32 v[224:225], v[224:225], v[104:105]
	v_pk_add_f32 v[226:227], v[226:227], v[140:141]
	v_cvt_pk_bf16_f32 v70, v70, v71
	v_cvt_pk_bf16_f32 v71, v72, v73
	v_cvt_pk_bf16_f32 v72, v74, v75
	v_cvt_pk_bf16_f32 v73, v76, v77
	v_cvt_pk_bf16_f32 v78, v78, v79
	v_cvt_pk_bf16_f32 v79, v80, v81
	v_cvt_pk_bf16_f32 v80, v82, v83
	v_cvt_pk_bf16_f32 v81, v84, v85
	v_cvt_pk_bf16_f32 v86, v86, v87
	v_cvt_pk_bf16_f32 v87, v88, v89
	v_cvt_pk_bf16_f32 v88, v90, v91
	v_cvt_pk_bf16_f32 v89, v92, v93
	v_cvt_pk_bf16_f32 v94, v94, v95
	v_cvt_pk_bf16_f32 v95, v96, v97
	v_cvt_pk_bf16_f32 v96, v98, v99
	v_cvt_pk_bf16_f32 v97, v100, v101
	v_cvt_pk_bf16_f32 v102, v102, v103
	v_cvt_pk_bf16_f32 v103, v104, v105
	v_mov_b32_e32 v104, 0
	v_mov_b32_e32 v105, 0
	v_cvt_pk_bf16_f32 v109, v108, v109
	v_cvt_pk_bf16_f32 v108, v106, v107
	v_mov_b32_e32 v106, 0
	v_mov_b32_e32 v107, 0
	v_cvt_pk_bf16_f32 v110, v110, v111
	v_cvt_pk_bf16_f32 v111, v112, v113
	v_cvt_pk_bf16_f32 v112, v114, v115
	v_cvt_pk_bf16_f32 v113, v116, v117
	v_cvt_pk_bf16_f32 v118, v118, v119
	v_cvt_pk_bf16_f32 v119, v120, v121
	v_cvt_pk_bf16_f32 v120, v122, v123
	v_cvt_pk_bf16_f32 v121, v124, v125
	v_cvt_pk_bf16_f32 v126, v126, v127
	v_cvt_pk_bf16_f32 v127, v128, v129
	v_cvt_pk_bf16_f32 v128, v130, v131
	v_cvt_pk_bf16_f32 v129, v132, v133
	v_cvt_pk_bf16_f32 v134, v134, v135
	v_cvt_pk_bf16_f32 v135, v136, v137
	v_cvt_pk_bf16_f32 v136, v138, v139
	v_cvt_pk_bf16_f32 v137, v140, v141
	s_add_i32 s17, s16, 0
	s_max_i32 s17, s17, 0
	s_lshl_b32 s17, s17, 11
	v_add_u32_e32 v142, s17, v230
	v_add_u32_e32 v143, s17, v231
	ds_read_b64_tr_b16 v[208:209], v142 offset:0
	ds_read_b64_tr_b16 v[210:211], v142 offset:2048
	ds_read_b64_tr_b16 v[212:213], v143 offset:0
	ds_read_b64_tr_b16 v[214:215], v143 offset:2048
	ds_read_b64_tr_b16 v[216:217], v142 offset:512
	ds_read_b64_tr_b16 v[218:219], v142 offset:2560
	ds_read_b64_tr_b16 v[220:221], v143 offset:512
	ds_read_b64_tr_b16 v[222:223], v143 offset:2560
	s_waitcnt lgkmcnt(6)
	v_mfma_f32_16x16x32_bf16 v[164:167], v[208:211], v[70:73], v[164:167]
	v_mfma_f32_16x16x32_bf16 v[168:171], v[208:211], v[106:109], v[168:171]
	s_add_i32 s17, s16, 2
	s_max_i32 s17, s17, 0
	s_lshl_b32 s17, s17, 11
	v_add_u32_e32 v144, s17, v230
	v_add_u32_e32 v145, s17, v231
	ds_read_b64_tr_b16 v[208:209], v144 offset:0
	ds_read_b64_tr_b16 v[210:211], v144 offset:2048
	s_waitcnt lgkmcnt(6)
	v_mfma_f32_16x16x32_bf16 v[172:175], v[212:215], v[70:73], v[172:175]
	v_mfma_f32_16x16x32_bf16 v[176:179], v[212:215], v[106:109], v[176:179]
	ds_read_b64_tr_b16 v[212:213], v145 offset:0
	ds_read_b64_tr_b16 v[214:215], v145 offset:2048
	s_waitcnt lgkmcnt(6)
	v_mfma_f32_16x16x32_bf16 v[180:183], v[216:219], v[70:73], v[180:183]
	v_mfma_f32_16x16x32_bf16 v[184:187], v[216:219], v[106:109], v[184:187]
	ds_read_b64_tr_b16 v[216:217], v144 offset:512
	ds_read_b64_tr_b16 v[218:219], v144 offset:2560
	s_waitcnt lgkmcnt(6)
	v_mfma_f32_16x16x32_bf16 v[188:191], v[220:223], v[70:73], v[188:191]
	v_mfma_f32_16x16x32_bf16 v[192:195], v[220:223], v[106:109], v[192:195]
	ds_read_b64_tr_b16 v[220:221], v145 offset:512
	ds_read_b64_tr_b16 v[222:223], v145 offset:2560
	s_waitcnt lgkmcnt(6)
	v_mfma_f32_16x16x32_bf16 v[164:167], v[208:211], v[78:81], v[164:167]
	v_mfma_f32_16x16x32_bf16 v[168:171], v[208:211], v[110:113], v[168:171]
	s_add_i32 s17, s16, 4
	s_max_i32 s17, s17, 0
	s_lshl_b32 s17, s17, 11
	v_add_u32_e32 v158, s17, v230
	v_add_u32_e32 v159, s17, v231
	ds_read_b64_tr_b16 v[208:209], v158 offset:0
	ds_read_b64_tr_b16 v[210:211], v158 offset:2048
	s_waitcnt lgkmcnt(6)
	v_mfma_f32_16x16x32_bf16 v[172:175], v[212:215], v[78:81], v[172:175]
	v_mfma_f32_16x16x32_bf16 v[176:179], v[212:215], v[110:113], v[176:179]
	ds_read_b64_tr_b16 v[212:213], v159 offset:0
	ds_read_b64_tr_b16 v[214:215], v159 offset:2048
	s_waitcnt lgkmcnt(6)
; #define LAS __attribute__((address_space(3)))
; __device__ __forceinline__ int crow(int r, int hi) { return (r & 3) + 8 * (r >> 2) + 4 * hi; }
; __device__ __forceinline__ unsigned cvtpk(float lo, float hi) { f32x2_cv v = {lo, hi}; bf16x2_cv b = __builtin_convertvector(v, bf16x2_cv); return __builtin_bit_cast(unsigned, b); }
; template <bool MLA> __device__ __forceinline__ void attn_unit(const AttnP& P, int b, int hh, int qb, LAS char* lds) {
;     ...
;     if (hi == 0) li_l[r32] = l_reg; asm volatile("s_waitcnt lgkmcnt(0)" ::: "memory");
;     bf16_t* Ow = (MLA ? P.QN + (rowbase + qlo) * 2048 + hh * 128 : P.QS + (rowbase + qlo) * 2048 + hh * 64);
; #pragma unroll
;     for (int r = 0; r < 16; ++r) { const int orow = crow(r, hi); const float rl = __builtin_amdgcn_rcpf(li_l[orow]);
; #pragma unroll
;         for (int d0 = 0; d0 < NCB; ++d0) { const float v = o[d0][r] * rl; const float vn = __shfl_xor(v, 1);
;             if ((r32 & 1) == 0) *(unsigned*)(Ow + (size_t)orow * 2048 + d0 * 32 + r32) = cvtpk(v, vn); } }
; __global__ void __launch_bounds__(512) fwd_mega(Args a) {
;     ...
;         for (int it = vcu; it < 4096; it += G) { const int qb = it & 63, hq = (it >> 6) & 31, b = it >> 11;
;             att::attn_unit<false>(P, b, hq, qb, (LAS char*)lds); }
	v_mfma_f32_16x16x32_bf16 v[180:183], v[216:219], v[78:81], v[180:183]
	v_mfma_f32_16x16x32_bf16 v[184:187], v[216:219], v[110:113], v[184:187]
	ds_read_b64_tr_b16 v[216:217], v158 offset:512
	ds_read_b64_tr_b16 v[218:219], v158 offset:2560
	s_waitcnt lgkmcnt(6)
	v_mfma_f32_16x16x32_bf16 v[188:191], v[220:223], v[78:81], v[188:191]
	v_mfma_f32_16x16x32_bf16 v[192:195], v[220:223], v[110:113], v[192:195]
	ds_read_b64_tr_b16 v[220:221], v159 offset:512
	ds_read_b64_tr_b16 v[222:223], v159 offset:2560
	s_waitcnt lgkmcnt(6)
	v_mfma_f32_16x16x32_bf16 v[164:167], v[208:211], v[86:89], v[164:167]
	v_mfma_f32_16x16x32_bf16 v[168:171], v[208:211], v[118:121], v[168:171]
	s_add_i32 s17, s16, 6
	s_max_i32 s17, s17, 0
	s_lshl_b32 s17, s17, 11
	v_add_u32_e32 v160, s17, v230
	v_add_u32_e32 v161, s17, v231
	ds_read_b64_tr_b16 v[208:209], v160 offset:0
	ds_read_b64_tr_b16 v[210:211], v160 offset:2048
	s_waitcnt lgkmcnt(6)
	v_mfma_f32_16x16x32_bf16 v[172:175], v[212:215], v[86:89], v[172:175]
	v_mfma_f32_16x16x32_bf16 v[176:179], v[212:215], v[118:121], v[176:179]
	ds_read_b64_tr_b16 v[212:213], v161 offset:0
	ds_read_b64_tr_b16 v[214:215], v161 offset:2048
	s_waitcnt lgkmcnt(6)
	v_mfma_f32_16x16x32_bf16 v[180:183], v[216:219], v[86:89], v[180:183]
	v_mfma_f32_16x16x32_bf16 v[184:187], v[216:219], v[118:121], v[184:187]
	ds_read_b64_tr_b16 v[216:217], v160 offset:512
	ds_read_b64_tr_b16 v[218:219], v160 offset:2560
	s_waitcnt lgkmcnt(6)
	v_mfma_f32_16x16x32_bf16 v[188:191], v[220:223], v[86:89], v[188:191]
	v_mfma_f32_16x16x32_bf16 v[192:195], v[220:223], v[118:121], v[192:195]
	ds_read_b64_tr_b16 v[220:221], v161 offset:512
	ds_read_b64_tr_b16 v[222:223], v161 offset:2560
	s_waitcnt lgkmcnt(6)
	v_mfma_f32_16x16x32_bf16 v[164:167], v[208:211], v[94:97], v[164:167]
	v_mfma_f32_16x16x32_bf16 v[168:171], v[208:211], v[126:129], v[168:171]
	s_add_i32 s17, s16, 8
	s_max_i32 s17, s17, 0
	s_lshl_b32 s17, s17, 11
	v_add_u32_e32 v204, s17, v230
	v_add_u32_e32 v207, s17, v231
	ds_read_b64_tr_b16 v[208:209], v204 offset:0
	ds_read_b64_tr_b16 v[210:211], v204 offset:2048
	s_waitcnt lgkmcnt(6)
	v_mfma_f32_16x16x32_bf16 v[172:175], v[212:215], v[94:97], v[172:175]
	v_mfma_f32_16x16x32_bf16 v[176:179], v[212:215], v[126:129], v[176:179]
	ds_read_b64_tr_b16 v[212:213], v207 offset:0
	ds_read_b64_tr_b16 v[214:215], v207 offset:2048
	s_waitcnt lgkmcnt(6)
	v_mfma_f32_16x16x32_bf16 v[180:183], v[216:219], v[94:97], v[180:183]
	v_mfma_f32_16x16x32_bf16 v[184:187], v[216:219], v[126:129], v[184:187]
	ds_read_b64_tr_b16 v[216:217], v204 offset:512
	ds_read_b64_tr_b16 v[218:219], v204 offset:2560
	s_waitcnt lgkmcnt(6)
	v_mfma_f32_16x16x32_bf16 v[188:191], v[220:223], v[94:97], v[188:191]
	v_mfma_f32_16x16x32_bf16 v[192:195], v[220:223], v[126:129], v[192:195]
	ds_read_b64_tr_b16 v[220:221], v207 offset:512
	ds_read_b64_tr_b16 v[222:223], v207 offset:2560
	s_waitcnt lgkmcnt(6)
	v_mfma_f32_16x16x32_bf16 v[164:167], v[208:211], v[102:105], v[164:167]
	v_mfma_f32_16x16x32_bf16 v[168:171], v[208:211], v[134:137], v[168:171]
	s_waitcnt lgkmcnt(4)
	v_mfma_f32_16x16x32_bf16 v[172:175], v[212:215], v[102:105], v[172:175]
	v_mfma_f32_16x16x32_bf16 v[176:179], v[212:215], v[134:137], v[176:179]
	s_waitcnt lgkmcnt(2)
	v_mfma_f32_16x16x32_bf16 v[180:183], v[216:219], v[102:105], v[180:183]
	v_mfma_f32_16x16x32_bf16 v[184:187], v[216:219], v[134:137], v[184:187]
	s_waitcnt lgkmcnt(0)
	v_mfma_f32_16x16x32_bf16 v[188:191], v[220:223], v[102:105], v[188:191]
	v_mfma_f32_16x16x32_bf16 v[192:195], v[220:223], v[134:137], v[192:195]
	v_add_f32_e32 v224, v224, v225
	v_add_f32_e32 v226, v226, v227
	ds_bpermute_b32 v240, v236, v224
	ds_bpermute_b32 v241, v236, v226
	s_waitcnt lgkmcnt(0)
	v_add_f32_e32 v224, v224, v240
	v_add_f32_e32 v226, v226, v241
	ds_bpermute_b32 v240, v237, v224
	ds_bpermute_b32 v241, v237, v226
	s_waitcnt lgkmcnt(0)
	v_add_f32_e32 v224, v224, v240
	v_add_f32_e32 v226, v226, v241
	v_mov_b32_e32 v242, s28
	v_fma_f32 v242, v242, s29, v156
	v_exp_f32_e32 v242, v242
	s_nop 0
	v_add_f32_e32 v224, v224, v242
	v_rcp_f32_e32 v224, v224
	v_mov_b32_e32 v243, s28
	v_fma_f32 v243, v243, s29, v157
	v_exp_f32_e32 v243, v243
	s_nop 0
	v_add_f32_e32 v226, v226, v243
	v_rcp_f32_e32 v226, v226
	s_nop 7
	v_mul_f32_e32 v164, v164, v224
	v_mul_f32_e32 v165, v165, v224
	v_mul_f32_e32 v166, v166, v224
	v_mul_f32_e32 v167, v167, v224
	v_cvt_pk_bf16_f32 v164, v164, v165
	v_cvt_pk_bf16_f32 v165, v166, v167
	global_store_dwordx2 v234, v[164:165], s[50:51] offset:0
	v_mul_f32_e32 v168, v168, v226
	v_mul_f32_e32 v169, v169, v226
	v_mul_f32_e32 v170, v170, v226
	v_mul_f32_e32 v171, v171, v226
	v_cvt_pk_bf16_f32 v168, v168, v169
	v_cvt_pk_bf16_f32 v169, v170, v171
	global_store_dwordx2 v197, v[168:169], s[50:51] offset:0
	v_mul_f32_e32 v172, v172, v224
	v_mul_f32_e32 v173, v173, v224
	v_mul_f32_e32 v174, v174, v224
	v_mul_f32_e32 v175, v175, v224
	v_cvt_pk_bf16_f32 v172, v172, v173
	v_cvt_pk_bf16_f32 v173, v174, v175
	global_store_dwordx2 v234, v[172:173], s[50:51] offset:32
	v_mul_f32_e32 v176, v176, v226
	v_mul_f32_e32 v177, v177, v226
	v_mul_f32_e32 v178, v178, v226
	v_mul_f32_e32 v179, v179, v226
	v_cvt_pk_bf16_f32 v176, v176, v177
	v_cvt_pk_bf16_f32 v177, v178, v179
	global_store_dwordx2 v197, v[176:177], s[50:51] offset:32
	v_mul_f32_e32 v180, v180, v224
	v_mul_f32_e32 v181, v181, v224
	v_mul_f32_e32 v182, v182, v224
	v_mul_f32_e32 v183, v183, v224
	v_cvt_pk_bf16_f32 v180, v180, v181
	v_cvt_pk_bf16_f32 v181, v182, v183
	global_store_dwordx2 v234, v[180:181], s[50:51] offset:64
	v_mul_f32_e32 v184, v184, v226
	v_mul_f32_e32 v185, v185, v226
	v_mul_f32_e32 v186, v186, v226
	v_mul_f32_e32 v187, v187, v226
	v_cvt_pk_bf16_f32 v184, v184, v185
	v_cvt_pk_bf16_f32 v185, v186, v187
	global_store_dwordx2 v197, v[184:185], s[50:51] offset:64
	v_mul_f32_e32 v188, v188, v224
	v_mul_f32_e32 v189, v189, v224
	v_mul_f32_e32 v190, v190, v224
	v_mul_f32_e32 v191, v191, v224
	v_cvt_pk_bf16_f32 v188, v188, v189
	v_cvt_pk_bf16_f32 v189, v190, v191
	global_store_dwordx2 v234, v[188:189], s[50:51] offset:96
	v_mul_f32_e32 v192, v192, v226
	v_mul_f32_e32 v193, v193, v226
	v_mul_f32_e32 v194, v194, v226
	v_mul_f32_e32 v195, v195, v226
	v_cvt_pk_bf16_f32 v192, v192, v193
	v_cvt_pk_bf16_f32 v193, v194, v195
	global_store_dwordx2 v197, v[192:193], s[50:51] offset:96
	s_add_u32 s2, s2, 0x100
	s_cmp_lt_u32 s6, 7
	s_cbranch_scc1 .Lsw_item
	s_branch .Lsw_fetch
.Lsw_end:
	s_waitcnt vmcnt(0) lgkmcnt(0)
	s_barrier
.LBB0_682:
	s_cmp_gt_i32 s55, 4
	s_cselect_b64 s[0:1], -1, 0
	s_and_b64 s[4:5], s[44:45], s[0:1]
	v_readlane_b32 s76, v253, 26
	s_andn2_b64 vcc, exec, s[4:5]
	v_readlane_b32 s77, v253, 27
	v_readlane_b32 s80, v253, 30
	v_readlane_b32 s81, v253, 31
	v_readlane_b32 s82, v253, 32
	v_readlane_b32 s83, v253, 33
	v_readlane_b32 s84, v253, 34
	v_readlane_b32 s85, v253, 35
	v_readlane_b32 s94, v253, 48
	v_readlane_b32 s78, v253, 28
	v_readlane_b32 s79, v253, 29
	v_readlane_b32 s86, v253, 36
	v_readlane_b32 s87, v253, 37
	v_readlane_b32 s88, v253, 38
	v_readlane_b32 s89, v253, 39
	v_readlane_b32 s90, v253, 40
	v_readlane_b32 s91, v253, 41
	s_cbranch_vccnz .LBB0_698
	s_waitcnt vmcnt(0) lgkmcnt(0)
	s_barrier
	v_readfirstlane_b32 s98, v162
	s_nop 3
	s_cmp_lt_u32 s98, 64
	s_cbranch_scc0 .Lsm3_wait
	buffer_wbl2 sc1
	s_waitcnt vmcnt(0)
	s_mov_b64 vcc, exec
	s_mov_b64 exec, 1
	s_and_b32 s98, s60, 7
	s_lshl_b32 s98, s98, 8
	s_add_u32 s98, s98, 0x400
	v_mov_b32_e32 v254, s98
	v_mov_b32_e32 v255, 1
	global_atomic_add v254, v255, s[52:53]
	s_mov_b64 exec, 0xff
	v_mbcnt_lo_u32_b32 v254, -1, 0
	v_lshlrev_b32_e32 v254, 8, v254
	v_add_u32_e32 v254, 0x400, v254
	s_lshr_b32 s99, s56, 3
	s_mul_i32 s99, s99, 3
	s_mov_b32 s100, 0
